# attn0 plain loop step B: only the score scale-shift ops reading the first accumulator precede the first QK^T MFMA; the rest run behind it
# speedup vs baseline: 1.0025x; 1.0025x over previous
.Lattn0_backA:
	s_waitcnt vmcnt(4) lgkmcnt(0)
	s_barrier
	v_add3_u32 v215, s69, v209, v208
	v_add3_u32 v216, s69, v210, v208
	v_add3_u32 v233, s69, v211, v208
	v_add3_u32 v254, s69, v212, v208
	ds_read_b128 v[234:237], v215 offset:49152
	ds_read_b128 v[238:241], v215 offset:57344
	ds_read_b128 v[242:245], v216 offset:49152
	ds_read_b128 v[246:249], v216 offset:57344
	ds_read_b128 v[250:253], v233 offset:49152
	v_mul_f32_e32 v5, 0xbe0293ee, v2
	v_fmamk_f32 v6, v112, 0x3e0293ee, v5
	v_fmamk_f32 v7, v113, 0x3e0293ee, v5
	v_fmamk_f32 v8, v114, 0x3e0293ee, v5
	v_fmamk_f32 v9, v115, 0x3e0293ee, v5
	v_fmamk_f32 v10, v116, 0x3e0293ee, v5
	v_fmamk_f32 v11, v117, 0x3e0293ee, v5
	v_fmamk_f32 v12, v118, 0x3e0293ee, v5
	v_fmamk_f32 v13, v119, 0x3e0293ee, v5
	v_fmamk_f32 v14, v120, 0x3e0293ee, v5
	v_fmamk_f32 v15, v121, 0x3e0293ee, v5
	v_fmamk_f32 v18, v122, 0x3e0293ee, v5
	v_fmamk_f32 v19, v123, 0x3e0293ee, v5
	v_fmamk_f32 v20, v124, 0x3e0293ee, v5
	v_fmamk_f32 v21, v125, 0x3e0293ee, v5
	v_fmamk_f32 v22, v126, 0x3e0293ee, v5
	v_fmamk_f32 v23, v127, 0x3e0293ee, v5
	s_setprio 1
	s_waitcnt lgkmcnt(4)
	v_mfma_f32_32x32x16_bf16 v[112:127], v[234:237], v[188:191], 0
	ds_read_b128 v[234:237], v233 offset:57344
	v_fmamk_f32 v24, v96, 0x3e0293ee, v5
	v_fmamk_f32 v25, v97, 0x3e0293ee, v5
	v_fmamk_f32 v26, v98, 0x3e0293ee, v5
	v_fmamk_f32 v27, v99, 0x3e0293ee, v5
	v_fmamk_f32 v28, v100, 0x3e0293ee, v5
	v_fmamk_f32 v29, v101, 0x3e0293ee, v5
	v_fmamk_f32 v30, v102, 0x3e0293ee, v5
	v_fmamk_f32 v31, v103, 0x3e0293ee, v5
	v_fmamk_f32 v128, v104, 0x3e0293ee, v5
	v_fmamk_f32 v129, v105, 0x3e0293ee, v5
	v_fmamk_f32 v130, v106, 0x3e0293ee, v5
	v_fmamk_f32 v131, v107, 0x3e0293ee, v5
	v_fmamk_f32 v132, v108, 0x3e0293ee, v5
	v_fmamk_f32 v133, v109, 0x3e0293ee, v5
	v_fmamk_f32 v134, v110, 0x3e0293ee, v5
	v_fmac_f32_e32 v5, 0x3e0293ee, v111
	v_exp_f32_e32 v135, v6
	v_exp_f32_e32 v136, v7
	v_exp_f32_e32 v137, v8
	v_exp_f32_e32 v138, v9
	s_waitcnt lgkmcnt(4)
	v_mfma_f32_32x32x16_bf16 v[96:111], v[238:241], v[188:191], 0
	ds_read_b128 v[238:241], v254 offset:49152
	v_exp_f32_e32 v10, v10
	v_exp_f32_e32 v11, v11
	v_exp_f32_e32 v12, v12
	s_waitcnt lgkmcnt(4)
	v_mfma_f32_32x32x16_bf16 v[112:127], v[242:245], v[184:187], v[112:127]
	ds_read_b128 v[242:245], v254 offset:57344
	s_add_i32 s4, s77, s42
	s_mov_b32 s5, m0
	s_mov_b32 m0, s4
	s_nop 0
	global_load_lds_dwordx4 v197, s[70:71]
	s_mov_b32 m0, s5
	v_exp_f32_e32 v13, v13
	v_exp_f32_e32 v14, v14
	v_exp_f32_e32 v15, v15
	v_exp_f32_e32 v18, v18
	s_waitcnt lgkmcnt(4)
	v_mfma_f32_32x32x16_bf16 v[96:111], v[246:249], v[184:187], v[96:111]
	ds_read_b128 v[246:249], v215 offset:49280
	v_exp_f32_e32 v19, v19
	v_exp_f32_e32 v20, v20
	v_exp_f32_e32 v21, v21
	s_waitcnt lgkmcnt(4)
	v_mfma_f32_32x32x16_bf16 v[112:127], v[250:253], v[180:183], v[112:127]
	ds_read_b128 v[250:253], v215 offset:57472
	v_exp_f32_e32 v22, v22
	v_exp_f32_e32 v23, v23
	v_exp_f32_e32 v7, v24
	v_exp_f32_e32 v24, v25
	s_waitcnt lgkmcnt(4)
	v_mfma_f32_32x32x16_bf16 v[96:111], v[234:237], v[180:183], v[96:111]
	ds_read_b128 v[234:237], v216 offset:49280
	s_addk_i32 s4, 0x400
	s_mov_b32 s5, m0
	s_mov_b32 m0, s4
	s_nop 0
	global_load_lds_dwordx4 v198, s[70:71]
	s_mov_b32 m0, s5
	v_exp_f32_e32 v25, v26
	v_exp_f32_e32 v26, v27
	v_exp_f32_e32 v27, v28
	s_waitcnt lgkmcnt(4)
	v_mfma_f32_32x32x16_bf16 v[112:127], v[238:241], v[176:179], v[112:127]
	ds_read_b128 v[238:241], v216 offset:57472
	v_exp_f32_e32 v28, v29
	v_exp_f32_e32 v29, v30
	v_exp_f32_e32 v30, v31
	v_exp_f32_e32 v31, v128
	s_waitcnt lgkmcnt(4)
	v_mfma_f32_32x32x16_bf16 v[96:111], v[242:245], v[176:179], v[96:111]
	ds_read_b128 v[242:245], v233 offset:49280
	v_exp_f32_e32 v128, v129
	v_exp_f32_e32 v129, v130
	v_exp_f32_e32 v130, v131
	v_exp_f32_e32 v131, v132
	s_waitcnt lgkmcnt(4)
	v_mfma_f32_32x32x16_bf16 v[112:127], v[246:249], v[172:175], v[112:127]
	ds_read_b128 v[246:249], v233 offset:57472
	s_add_u32 s4, s56, 0x4000
	s_addc_u32 s5, s57, 0
	s_add_i32 s72, s74, s97
	s_mov_b32 s73, m0
	s_mov_b32 m0, s72
	s_nop 0
	global_load_lds_dwordx4 v199, s[4:5]
	s_mov_b32 m0, s73
	v_exp_f32_e32 v132, v133
	v_exp_f32_e32 v133, v134
	v_exp_f32_e32 v134, v5
	s_waitcnt lgkmcnt(4)
	v_mfma_f32_32x32x16_bf16 v[96:111], v[250:253], v[172:175], v[96:111]
	ds_read_b128 v[250:253], v254 offset:49280
	v_add_f32_e32 v5, 0, v135
	v_add_f32_e32 v5, v136, v5
	v_add_f32_e32 v5, v137, v5
	v_add_f32_e32 v5, v138, v5
	v_add_f32_e32 v5, v10, v5
	v_add_f32_e32 v5, v11, v5
	v_add_f32_e32 v5, v12, v5
	v_add_f32_e32 v5, v13, v5
	s_waitcnt lgkmcnt(4)
	v_mfma_f32_32x32x16_bf16 v[112:127], v[234:237], v[168:171], v[112:127]
	ds_read_b128 v[234:237], v254 offset:57472
	v_add_f32_e32 v5, v14, v5
	v_add_f32_e32 v5, v15, v5
	v_add_f32_e32 v5, v18, v5
	v_add_f32_e32 v5, v19, v5
	v_add_f32_e32 v5, v20, v5
	v_add_f32_e32 v5, v21, v5
	v_add_f32_e32 v5, v22, v5
	s_waitcnt lgkmcnt(4)
	v_mfma_f32_32x32x16_bf16 v[96:111], v[238:241], v[168:171], v[96:111]
	s_addk_i32 s72, 0x400
	s_mov_b32 s73, m0
	s_mov_b32 m0, s72
	s_nop 0
	global_load_lds_dwordx4 v200, s[4:5]
	s_mov_b32 m0, s73
	v_add_f32_e32 v5, v23, v5
	v_add_f32_e32 v5, v7, v5
	v_add_f32_e32 v5, v24, v5
	v_add_f32_e32 v5, v25, v5
	v_add_f32_e32 v5, v26, v5
	v_add_f32_e32 v5, v27, v5
	v_add_f32_e32 v5, v28, v5
	s_waitcnt lgkmcnt(3)
	v_mfma_f32_32x32x16_bf16 v[112:127], v[242:245], v[164:167], v[112:127]
	v_add_f32_e32 v5, v29, v5
	v_add_f32_e32 v5, v30, v5
	v_add_f32_e32 v5, v31, v5
	v_add_f32_e32 v5, v128, v5
	v_add_f32_e32 v5, v129, v5
	v_add_f32_e32 v5, v130, v5
	v_add_f32_e32 v5, v131, v5
	s_waitcnt lgkmcnt(2)
	v_mfma_f32_32x32x16_bf16 v[96:111], v[246:249], v[164:167], v[96:111]
	v_add_f32_e32 v5, v132, v5
	v_add_f32_e32 v5, v133, v5
	v_add_f32_e32 v5, v134, v5
	v_mov_b32_e32 v6, v5
	v_cvt_pk_bf16_f32 v8, v135, v136
	v_cvt_pk_bf16_f32 v9, v137, v138
	v_cvt_pk_bf16_f32 v10, v10, v11
	s_waitcnt lgkmcnt(1)
	v_mfma_f32_32x32x16_bf16 v[112:127], v[250:253], v[160:163], v[112:127]
	s_nop 1
	v_permlane32_swap_b32_e32 v5, v6
	v_cvt_pk_bf16_f32 v11, v12, v13
	v_cvt_pk_bf16_f32 v12, v14, v15
	v_cvt_pk_bf16_f32 v13, v18, v19
	v_cvt_pk_bf16_f32 v14, v20, v21
	v_cvt_pk_bf16_f32 v15, v22, v23
	v_cvt_pk_bf16_f32 v18, v7, v24
	s_waitcnt lgkmcnt(0)
	v_mfma_f32_32x32x16_bf16 v[96:111], v[234:237], v[160:163], v[96:111]
	v_cvt_pk_bf16_f32 v19, v25, v26
	v_cvt_pk_bf16_f32 v20, v27, v28
	v_cvt_pk_bf16_f32 v21, v29, v30
	v_cvt_pk_bf16_f32 v22, v31, v128
	v_cvt_pk_bf16_f32 v23, v129, v130
	v_cvt_pk_bf16_f32 v24, v131, v132
	v_cvt_pk_bf16_f32 v25, v133, v134
	s_setprio 0
	v_add_u32_e32 v7, s77, v206
	ds_read_b64_tr_b16 v[26:27], v7 offset:0
	ds_read_b64_tr_b16 v[28:29], v7 offset:0x800
	ds_read_b64_tr_b16 v[128:129], v7 offset:0x1000
	ds_read_b64_tr_b16 v[130:131], v7 offset:0x1800
	ds_read_b64_tr_b16 v[132:133], v7 offset:0x2000
	ds_read_b64_tr_b16 v[134:135], v7 offset:0x2800
	ds_read_b64_tr_b16 v[136:137], v7 offset:0x3000
	ds_read_b64_tr_b16 v[138:139], v7 offset:0x3800
	s_waitcnt lgkmcnt(6)
	s_nop 0
	v_mfma_f32_32x32x16_bf16 v[32:47], v[8:11], v[26:29], v[32:47]
	ds_read_b64_tr_b16 v[26:27], v7 offset:0x200
	ds_read_b64_tr_b16 v[28:29], v7 offset:0xa00
	s_waitcnt lgkmcnt(6)
	v_mfma_f32_32x32x16_bf16 v[32:47], v[12:15], v[128:131], v[32:47]
	ds_read_b64_tr_b16 v[128:129], v7 offset:0x1200
	ds_read_b64_tr_b16 v[130:131], v7 offset:0x1a00
	s_waitcnt lgkmcnt(6)
	v_mfma_f32_32x32x16_bf16 v[32:47], v[18:21], v[132:135], v[32:47]
	ds_read_b64_tr_b16 v[132:133], v7 offset:0x2200
	ds_read_b64_tr_b16 v[134:135], v7 offset:0x2a00
	s_waitcnt lgkmcnt(6)
	v_mfma_f32_32x32x16_bf16 v[32:47], v[22:25], v[136:139], v[32:47]
	ds_read_b64_tr_b16 v[136:137], v7 offset:0x3200
	ds_read_b64_tr_b16 v[138:139], v7 offset:0x3a00
	s_waitcnt lgkmcnt(6)
	v_mfma_f32_32x32x16_bf16 v[48:63], v[8:11], v[26:29], v[48:63]
	ds_read_b64_tr_b16 v[26:27], v7 offset:0x400
	ds_read_b64_tr_b16 v[28:29], v7 offset:0xc00
	s_waitcnt lgkmcnt(6)
	v_mfma_f32_32x32x16_bf16 v[48:63], v[12:15], v[128:131], v[48:63]
	ds_read_b64_tr_b16 v[128:129], v7 offset:0x1400
	ds_read_b64_tr_b16 v[130:131], v7 offset:0x1c00
	s_waitcnt lgkmcnt(6)
	v_mfma_f32_32x32x16_bf16 v[48:63], v[18:21], v[132:135], v[48:63]
	ds_read_b64_tr_b16 v[132:133], v7 offset:0x2400
	ds_read_b64_tr_b16 v[134:135], v7 offset:0x2c00
	s_waitcnt lgkmcnt(6)
	v_mfma_f32_32x32x16_bf16 v[48:63], v[22:25], v[136:139], v[48:63]
	ds_read_b64_tr_b16 v[136:137], v7 offset:0x3400
	ds_read_b64_tr_b16 v[138:139], v7 offset:0x3c00
	s_waitcnt lgkmcnt(6)
	v_mfma_f32_32x32x16_bf16 v[64:79], v[8:11], v[26:29], v[64:79]
	ds_read_b64_tr_b16 v[26:27], v7 offset:0x600
	ds_read_b64_tr_b16 v[28:29], v7 offset:0xe00
	s_waitcnt lgkmcnt(6)
	v_mfma_f32_32x32x16_bf16 v[64:79], v[12:15], v[128:131], v[64:79]
	ds_read_b64_tr_b16 v[128:129], v7 offset:0x1600
	ds_read_b64_tr_b16 v[130:131], v7 offset:0x1e00
	s_waitcnt lgkmcnt(6)
	v_mfma_f32_32x32x16_bf16 v[64:79], v[18:21], v[132:135], v[64:79]
	ds_read_b64_tr_b16 v[132:133], v7 offset:0x2600
	ds_read_b64_tr_b16 v[134:135], v7 offset:0x2e00
	s_waitcnt lgkmcnt(6)
	v_mfma_f32_32x32x16_bf16 v[64:79], v[22:25], v[136:139], v[64:79]
	ds_read_b64_tr_b16 v[136:137], v7 offset:0x3600
	ds_read_b64_tr_b16 v[138:139], v7 offset:0x3e00
	s_waitcnt lgkmcnt(6)
	v_mfma_f32_32x32x16_bf16 v[80:95], v[8:11], v[26:29], v[80:95]
	v_max_f32_e32 v7, v113, v112
	v_max3_f32 v7, v7, v114, v115
	v_max3_f32 v7, v7, v116, v117
	v_max3_f32 v7, v7, v118, v119
	v_max3_f32 v7, v7, v120, v121
	v_max3_f32 v7, v7, v122, v123
	v_max3_f32 v7, v7, v124, v125
	v_max3_f32 v7, v7, v126, v127
	s_waitcnt lgkmcnt(4)
	v_mfma_f32_32x32x16_bf16 v[80:95], v[12:15], v[128:131], v[80:95]
	v_max3_f32 v7, v7, v96, v97
	v_max3_f32 v7, v7, v98, v99
	v_max3_f32 v7, v7, v100, v101
	v_max3_f32 v7, v7, v102, v103
	v_max3_f32 v7, v7, v104, v105
	v_max3_f32 v7, v7, v106, v107
	v_max3_f32 v7, v7, v108, v109
	v_max3_f32 v7, v7, v110, v111
	s_waitcnt lgkmcnt(2)
	v_mfma_f32_32x32x16_bf16 v[80:95], v[18:21], v[132:135], v[80:95]
	v_mov_b32_e32 v8, v7
	s_nop 1
	v_permlane32_swap_b32_e32 v7, v8
	v_max_f32_e32 v7, v8, v7
	v_sub_f32_e32 v8, v7, v2
	v_cmp_ge_f32_e32 vcc, 0x42b504f3, v8
	v_max_f32_e32 v8, v2, v7
	s_waitcnt lgkmcnt(0)
	v_mfma_f32_32x32x16_bf16 v[80:95], v[22:25], v[136:139], v[80:95]
	s_cmp_eq_u64 vcc, exec
	s_cbranch_scc0 .Lattn0_slowB
	v_mov_b32_e32 v7, 1.0
	v_mov_b32_e32 v214, v2
